# SSD pass C: hoist per-head XdT/StL/D/x/z global loads ahead of their consumers (counted vmcnt), unroll 2-iteration StL loop
# speedup vs baseline: 1.0623x; 1.0056x over previous
.LBB0_651:
	s_lshl_b32 s78, s96, 7
	v_lshl_add_u64 v[254:255], v[72:73], 0, s[78:79]
	global_load_dwordx4 v[236:239], v[254:255], off offset:16
	global_load_dwordx4 v[240:243], v[254:255], off
	s_mov_b64 s[100:101], 0x2000
	global_load_dwordx4 v[244:247], v[80:81], off
	v_lshl_add_u64 v[254:255], v[80:81], 0, s[100:101]
	global_load_dwordx4 v[248:251], v[254:255], off
	s_add_i32 s98, s96, s68
	s_lshl_b32 s98, s98, 2
	v_readlane_b32 s100, v235, 23
	v_readlane_b32 s101, v235, 24
	s_nop 3
	s_add_u32 s100, s100, s98
	s_addc_u32 s101, s101, 0
	global_load_dword v252, v65, s[100:101]
	s_lshl_b32 s0, s96, 9
	s_add_i32 s0, s0, 0
	v_lshl_add_u32 v32, v67, 2, s0
	v_lshl_add_u32 v33, v94, 2, s0
	v_mov_b32_e32 v34, 0
	s_and_saveexec_b64 s[0:1], s[2:3]
	s_cbranch_execz .LBB0_653
	ds_read_b32 v34, v33 offset:4096
	ds_read_b32 v35, v32 offset:4096
	s_waitcnt lgkmcnt(0)
	v_sub_f32_e32 v34, v34, v35
	v_mul_f32_e32 v34, 0x3fb8aa3b, v34
	v_exp_f32_e32 v34, v34
	s_nop 0
	v_mul_f32_e32 v34, v0, v34
	v_cvt_pk_bf16_f32 v34, v34, s0

.LBB0_715:
	s_or_b64 exec, exec, s[0:1]
	s_lshl_b32 s78, s96, 7
	ds_write_b16 v119, v34 offset:44048
	v_lshl_add_u32 v48, s78, 2, v95
	ds_read_b32 v48, v48
	s_lshl_b32 s0, s96, 6
	s_mov_b64 s[94:95], 0
	s_waitcnt vmcnt(4)
	v_lshlrev_b32_e32 v44, 16, v236
	v_and_b32_e32 v32, 0xffff0000, v236
	s_waitcnt lgkmcnt(0)
	v_mul_f32_e32 v32, v48, v32
	s_waitcnt vmcnt(3)
	v_lshlrev_b32_e32 v41, 16, v241
	v_cvt_pk_bf16_f32 v32, v32, s0
	ds_write_b16 v102, v32 offset:2176
	v_mul_f32_e32 v32, v48, v41
	v_lshlrev_b32_e32 v45, 16, v237
	v_cvt_pk_bf16_f32 v32, v32, s0
	ds_write_b16 v100, v32 offset:544
	v_mul_f32_e32 v32, v48, v45
	v_and_b32_e32 v37, 0xffff0000, v241
	v_cvt_pk_bf16_f32 v32, v32, s0
	ds_write_b16 v103, v32 offset:2176
	v_mul_f32_e32 v32, v48, v37
	v_and_b32_e32 v33, 0xffff0000, v237
	v_cvt_pk_bf16_f32 v32, v32, s0
	ds_write_b16 v100, v32 offset:816
	v_mul_f32_e32 v32, v48, v33
	v_lshlrev_b32_e32 v42, 16, v242
	v_cvt_pk_bf16_f32 v32, v32, s0
	ds_write_b16 v104, v32 offset:2176
	v_mul_f32_e32 v32, v48, v42
	v_lshlrev_b32_e32 v46, 16, v238
	v_cvt_pk_bf16_f32 v32, v32, s0
	ds_write_b16 v100, v32 offset:1088
	v_mul_f32_e32 v32, v48, v46
	v_and_b32_e32 v38, 0xffff0000, v242
	v_cvt_pk_bf16_f32 v32, v32, s0
	ds_write_b16 v105, v32 offset:2176
	v_mul_f32_e32 v32, v48, v38
	v_and_b32_e32 v34, 0xffff0000, v238
	v_cvt_pk_bf16_f32 v32, v32, s0
	ds_write_b16 v100, v32 offset:1360
	v_mul_f32_e32 v32, v48, v34
	v_lshlrev_b32_e32 v43, 16, v243
	v_cvt_pk_bf16_f32 v32, v32, s0
	ds_write_b16 v106, v32 offset:2176
	v_mul_f32_e32 v32, v48, v43
	v_lshlrev_b32_e32 v47, 16, v239
	v_cvt_pk_bf16_f32 v32, v32, s0
	ds_write_b16 v100, v32 offset:1632
	v_mul_f32_e32 v32, v48, v47
	v_and_b32_e32 v39, 0xffff0000, v243
	v_cvt_pk_bf16_f32 v32, v32, s0
	v_lshlrev_b32_e32 v40, 16, v240
	ds_write_b16 v107, v32 offset:2176
	v_mul_f32_e32 v32, v48, v39
	v_and_b32_e32 v35, 0xffff0000, v239
	v_mul_f32_e32 v40, v48, v40
	v_cvt_pk_bf16_f32 v32, v32, s0
	v_and_b32_e32 v36, 0xffff0000, v240
	v_cvt_pk_bf16_f32 v40, v40, s0
	ds_write_b16 v100, v32 offset:1904
	v_mul_f32_e32 v32, v48, v35
	ds_write_b16 v100, v40
	v_mul_f32_e32 v40, v48, v44
	v_mul_f32_e32 v36, v48, v36
	v_cvt_pk_bf16_f32 v32, v32, s0
	v_cvt_pk_bf16_f32 v40, v40, s0
	v_cvt_pk_bf16_f32 v36, v36, s0
	ds_write_b16 v108, v32 offset:2176
	ds_write_b16 v101, v40 offset:2176
	ds_write_b16 v100, v36 offset:272
	s_waitcnt vmcnt(1)
	ds_write_b128 v114, v[244:247]
	ds_write_b128 v114, v[248:251] offset:8704
	v_add_lshl_u32 v253, s0, v71, 1
	v_add_co_u32_e32 v254, vcc, v76, v253
	s_nop 1
	v_addc_co_u32_e32 v255, vcc, 0, v77, vcc
	global_load_dwordx2 v[236:237], v[254:255], off
	global_load_dwordx2 v[238:239], v[254:255], off offset:32
	global_load_dwordx2 v[240:241], v[254:255], off offset:64
	global_load_dwordx2 v[242:243], v[254:255], off offset:96
	v_add_co_u32_e32 v254, vcc, v74, v253
	s_nop 1
	v_addc_co_u32_e32 v255, vcc, 0, v75, vcc
	global_load_dwordx2 v[244:245], v[254:255], off
	global_load_dwordx2 v[246:247], v[254:255], off offset:32
	global_load_dwordx2 v[248:249], v[254:255], off offset:64
	global_load_dwordx2 v[250:251], v[254:255], off offset:96
	s_waitcnt lgkmcnt(0)
	s_barrier
	ds_read_b128 v[32:35], v91 offset:43008
	ds_read_b128 v[36:39], v96
	ds_read_b128 v[40:43], v96 offset:4352
	ds_read_b128 v[44:47], v96 offset:8704
	ds_read_b128 v[48:51], v96 offset:13056
	s_waitcnt lgkmcnt(3)
	v_mfma_f32_16x16x32_bf16 v[36:39], v[36:39], v[32:35], 0
	v_lshl_add_u32 v64, s78, 2, v98
	s_add_i32 s94, s96, s68
	s_mov_b32 s95, s79
	s_waitcnt lgkmcnt(2)
	v_mfma_f32_16x16x32_bf16 v[40:43], v[40:43], v[32:35], 0
	s_lshl_b64 vcc, s[94:95], 2
	v_readlane_b32 s80, v235, 23
	v_readlane_b32 s94, v235, 37
	s_waitcnt lgkmcnt(1)
	v_mfma_f32_16x16x32_bf16 v[44:47], v[44:47], v[32:35], 0
	v_readlane_b32 s81, v235, 24
	v_readlane_b32 s95, v235, 38
	s_add_u32 s94, s80, vcc_lo
	s_waitcnt lgkmcnt(0)
	v_mfma_f32_16x16x32_bf16 v[32:35], v[48:51], v[32:35], 0
	ds_read_b128 v[48:51], v91 offset:43072
	ds_read_b128 v[52:55], v96 offset:64
	s_addc_u32 s95, s81, vcc_hi
	s_add_i32 s96, s96, 1
	s_waitcnt lgkmcnt(0)
	v_mfma_f32_16x16x32_bf16 v[36:39], v[52:55], v[48:51], v[36:39]
	ds_read_b128 v[52:55], v96 offset:4416
	s_cmp_eq_u32 s96, 8
	v_readlane_b32 s82, v235, 25
	s_waitcnt lgkmcnt(0)
	v_mfma_f32_16x16x32_bf16 v[40:43], v[52:55], v[48:51], v[40:43]
	ds_read_b128 v[52:55], v96 offset:8768
	v_readlane_b32 s83, v235, 26
	v_readlane_b32 s84, v235, 27
	s_waitcnt lgkmcnt(0)
	v_mfma_f32_16x16x32_bf16 v[44:47], v[52:55], v[48:51], v[44:47]
	ds_read_b128 v[52:55], v96 offset:13120
	v_readlane_b32 s85, v235, 28
	v_readlane_b32 s86, v235, 29
	s_waitcnt lgkmcnt(0)
	v_mfma_f32_16x16x32_bf16 v[32:35], v[52:55], v[48:51], v[32:35]
	ds_read_b128 v[48:51], v91 offset:43136
	ds_read_b128 v[52:55], v96 offset:128
	v_readlane_b32 s87, v235, 30
	v_readlane_b32 s88, v235, 31
	s_waitcnt lgkmcnt(0)
	v_mfma_f32_16x16x32_bf16 v[36:39], v[52:55], v[48:51], v[36:39]
	ds_read_b128 v[52:55], v96 offset:4480
	v_readlane_b32 s89, v235, 32
	v_readlane_b32 s90, v235, 33
	s_waitcnt lgkmcnt(0)
	v_mfma_f32_16x16x32_bf16 v[40:43], v[52:55], v[48:51], v[40:43]
	ds_read_b128 v[52:55], v96 offset:8832
	v_readlane_b32 s91, v235, 34
	v_readlane_b32 s92, v235, 35
	s_waitcnt lgkmcnt(0)
	v_mfma_f32_16x16x32_bf16 v[44:47], v[52:55], v[48:51], v[44:47]
	ds_read_b128 v[52:55], v96 offset:13184
	v_readlane_b32 s93, v235, 36
	s_waitcnt lgkmcnt(0)
	v_mfma_f32_16x16x32_bf16 v[32:35], v[52:55], v[48:51], v[32:35]
	ds_read_b128 v[52:55], v91 offset:43200
	ds_read_b128 v[48:51], v96 offset:192
	s_waitcnt lgkmcnt(0)
	v_mfma_f32_16x16x32_bf16 v[56:59], v[48:51], v[52:55], v[36:39]
	s_nop 2
	ds_read_b128 v[36:39], v96 offset:4544
	s_waitcnt lgkmcnt(0)
	v_mfma_f32_16x16x32_bf16 v[48:51], v[36:39], v[52:55], v[40:43]
	ds_read_b128 v[36:39], v96 offset:8896
	s_waitcnt lgkmcnt(0)
	v_mfma_f32_16x16x32_bf16 v[40:43], v[36:39], v[52:55], v[44:47]
	ds_read_b128 v[36:39], v96 offset:13248
	s_waitcnt lgkmcnt(0)
	v_mfma_f32_16x16x32_bf16 v[32:35], v[36:39], v[52:55], v[32:35]
	ds_read_b128 v[36:39], v91 offset:8192
	ds_read_b128 v[44:47], v97
	ds_read_b128 v[52:55], v97 offset:4352
	ds_read_b128 v[60:63], v97 offset:8704
	ds_read_b128 v[86:89], v97 offset:13056
	s_waitcnt lgkmcnt(3)
	v_mfma_f32_16x16x32_bf16 v[44:47], v[44:47], v[36:39], 0
	s_waitcnt lgkmcnt(2)
	v_mfma_f32_16x16x32_bf16 v[52:55], v[52:55], v[36:39], 0
	s_waitcnt lgkmcnt(1)
	v_mfma_f32_16x16x32_bf16 v[60:63], v[60:63], v[36:39], 0
	s_waitcnt lgkmcnt(0)
	v_mfma_f32_16x16x32_bf16 v[36:39], v[86:89], v[36:39], 0
	ds_read_b128 v[86:89], v91 offset:8256
	ds_read_b128 v[122:125], v97 offset:64
	s_waitcnt lgkmcnt(0)
	v_mfma_f32_16x16x32_bf16 v[44:47], v[122:125], v[86:89], v[44:47]
	ds_read_b128 v[122:125], v97 offset:4416
	s_waitcnt lgkmcnt(0)
	v_mfma_f32_16x16x32_bf16 v[52:55], v[122:125], v[86:89], v[52:55]
	ds_read_b128 v[122:125], v97 offset:8768
	s_waitcnt lgkmcnt(0)
	v_mfma_f32_16x16x32_bf16 v[60:63], v[122:125], v[86:89], v[60:63]
	ds_read_b128 v[122:125], v97 offset:13120
	s_waitcnt lgkmcnt(0)
	v_mfma_f32_16x16x32_bf16 v[36:39], v[122:125], v[86:89], v[36:39]
	ds_read_b128 v[86:89], v91 offset:8320
	ds_read_b128 v[122:125], v97 offset:128
	s_waitcnt lgkmcnt(0)
	v_mfma_f32_16x16x32_bf16 v[44:47], v[122:125], v[86:89], v[44:47]
	ds_read_b128 v[122:125], v97 offset:4480
	s_waitcnt lgkmcnt(0)
	v_mfma_f32_16x16x32_bf16 v[52:55], v[122:125], v[86:89], v[52:55]
	ds_read_b128 v[122:125], v97 offset:8832
	s_waitcnt lgkmcnt(0)
	v_mfma_f32_16x16x32_bf16 v[122:125], v[122:125], v[86:89], v[60:63]
	s_nop 2
	ds_read_b128 v[60:63], v97 offset:13184
	s_waitcnt lgkmcnt(0)
	v_mfma_f32_16x16x32_bf16 v[36:39], v[60:63], v[86:89], v[36:39]
	ds_read_b128 v[86:89], v91 offset:8384
	ds_read_b128 v[60:63], v97 offset:192
	ds_read_b32 v64, v64 offset:4096
	s_waitcnt lgkmcnt(1)
	v_mfma_f32_16x16x32_bf16 v[60:63], v[60:63], v[86:89], v[44:47]
	s_waitcnt lgkmcnt(0)
	v_mul_f32_e32 v64, 0x3fb8aa3b, v64
	s_nop 0
	ds_read_b128 v[44:47], v97 offset:4544
	v_exp_f32_e32 v82, v64
	s_waitcnt lgkmcnt(0)
	v_mfma_f32_16x16x32_bf16 v[52:55], v[44:47], v[86:89], v[52:55]
	ds_read_b128 v[44:47], v97 offset:8896
	v_add_lshl_u32 v64, s0, v71, 1
	v_pk_fma_f32 v[56:57], v[60:61], v[82:83], v[56:57] op_sel_hi:[1,0,1]
	s_waitcnt lgkmcnt(0)
	v_mfma_f32_16x16x32_bf16 v[44:47], v[44:47], v[86:89], v[122:125]
	s_nop 2
	ds_read_b128 v[122:125], v97 offset:13248
	v_pk_fma_f32 v[58:59], v[62:63], v[82:83], v[58:59] op_sel_hi:[1,0,1]
	v_pk_fma_f32 v[48:49], v[52:53], v[82:83], v[48:49] op_sel_hi:[1,0,1]
	s_waitcnt lgkmcnt(0)
	v_mfma_f32_16x16x32_bf16 v[36:39], v[122:125], v[86:89], v[36:39]
	v_lshl_add_u64 v[86:87], v[76:77], 0, v[64:65]
	v_lshl_add_u64 v[88:89], v[74:75], 0, v[64:65]
	v_pk_fma_f32 v[50:51], v[54:55], v[82:83], v[50:51] op_sel_hi:[1,0,1]
	v_pk_fma_f32 v[40:41], v[44:45], v[82:83], v[40:41] op_sel_hi:[1,0,1]
	v_pk_fma_f32 v[42:43], v[46:47], v[82:83], v[42:43] op_sel_hi:[1,0,1]
	s_nop 0
	v_pk_fma_f32 v[32:33], v[36:37], v[82:83], v[32:33] op_sel_hi:[1,0,1]
	v_pk_fma_f32 v[34:35], v[38:39], v[82:83], v[34:35] op_sel_hi:[1,0,1]
	s_mov_b64 s[0:1], 0x4000
	v_lshl_add_u64 v[80:81], v[80:81], 0, s[0:1]
	s_waitcnt vmcnt(7)
	v_lshlrev_b32_e32 v128, 16, v236
	v_and_b32_e32 v129, 0xffff0000, v236
	s_waitcnt vmcnt(3)
	v_lshlrev_b32_e32 v126, 16, v244
	v_and_b32_e32 v127, 0xffff0000, v244
	v_mul_f32_e32 v122, 0xbfb8aa3b, v128
	v_mul_f32_e32 v60, 0xbfb8aa3b, v129
	v_exp_f32_e32 v122, v122
	v_exp_f32_e32 v60, v60
	v_pk_fma_f32 v[56:57], v[252:253], v[126:127], v[56:57] op_sel_hi:[0,1,1]
	v_add_f32_e32 v122, 1.0, v122
	v_add_f32_e32 v60, 1.0, v60
	v_rcp_f32_e32 v130, v122
	v_rcp_f32_e32 v131, v60
	v_lshlrev_b32_e32 v122, 16, v237
	v_pk_mul_f32 v[60:61], v[130:131], v[128:129]
	s_nop 0
	v_pk_mul_f32 v[56:57], v[56:57], v[60:61]
	s_nop 0
	v_pk_mul_f32 v[60:61], v[56:57], v[56:57]
	s_nop 0
	v_add_f32_e32 v60, v121, v60
	v_add_f32_e32 v61, v61, v60
	v_cvt_pk_bf16_f32 v60, v56, v57
	v_lshlrev_b32_e32 v56, 16, v245
	v_and_b32_e32 v57, 0xffff0000, v245
	v_and_b32_e32 v123, 0xffff0000, v237
	v_mul_f32_e32 v121, 0xbfb8aa3b, v122
	v_pk_fma_f32 v[56:57], v[252:253], v[56:57], v[58:59] op_sel_hi:[0,1,1]
	v_mul_f32_e32 v58, 0xbfb8aa3b, v123
	v_exp_f32_e32 v121, v121
	v_exp_f32_e32 v58, v58
	v_add_f32_e32 v121, 1.0, v121
	v_add_f32_e32 v58, 1.0, v58
	v_rcp_f32_e32 v124, v121
	v_rcp_f32_e32 v125, v58
	s_nop 0
	v_pk_mul_f32 v[58:59], v[124:125], v[122:123]
	s_nop 0
	v_pk_mul_f32 v[56:57], v[56:57], v[58:59]
	s_nop 0
	v_pk_mul_f32 v[58:59], v[56:57], v[56:57]
	s_nop 0
	v_add_f32_e32 v58, v58, v61
	v_cvt_pk_bf16_f32 v61, v56, v57
	v_lshl_add_u64 v[56:57], v[78:79], 0, v[64:65]
	global_store_dwordx2 v[56:57], v[60:61], off
	v_add_f32_e32 v121, v59, v58
	s_waitcnt vmcnt(3)
	v_lshlrev_b32_e32 v62, 16, v246
	s_waitcnt vmcnt(7)
	v_lshlrev_b32_e32 v122, 16, v238
	v_and_b32_e32 v123, 0xffff0000, v238
	v_and_b32_e32 v63, 0xffff0000, v246
	v_mul_f32_e32 v58, 0xbfb8aa3b, v122
	v_mul_f32_e32 v52, 0xbfb8aa3b, v123
	v_exp_f32_e32 v58, v58
	v_exp_f32_e32 v52, v52
	v_pk_fma_f32 v[48:49], v[252:253], v[62:63], v[48:49] op_sel_hi:[0,1,1]
	v_add_f32_e32 v58, 1.0, v58
	v_add_f32_e32 v52, 1.0, v52
	v_rcp_f32_e32 v124, v58
	v_rcp_f32_e32 v125, v52
	v_lshlrev_b32_e32 v58, 16, v239
	v_pk_mul_f32 v[52:53], v[124:125], v[122:123]
	s_nop 0
	v_pk_mul_f32 v[48:49], v[48:49], v[52:53]
	s_nop 0
	v_pk_mul_f32 v[52:53], v[48:49], v[48:49]
	v_cvt_pk_bf16_f32 v48, v48, v49
	v_mul_f32_e32 v49, 0xbfb8aa3b, v58
	v_exp_f32_e32 v49, v49
	v_add_f32_e32 v52, v52, v121
	v_add_f32_e32 v62, v53, v52
	v_lshlrev_b32_e32 v52, 16, v247
	v_and_b32_e32 v53, 0xffff0000, v247
	v_and_b32_e32 v59, 0xffff0000, v239
	v_add_f32_e32 v49, 1.0, v49
	v_rcp_f32_e32 v60, v49
	v_mul_f32_e32 v49, 0xbfb8aa3b, v59
	v_exp_f32_e32 v49, v49
	v_pk_fma_f32 v[50:51], v[252:253], v[52:53], v[50:51] op_sel_hi:[0,1,1]
	v_add_f32_e32 v49, 1.0, v49
	v_rcp_f32_e32 v61, v49
	s_nop 0
	v_pk_mul_f32 v[52:53], v[60:61], v[58:59]
	s_nop 0
	v_pk_mul_f32 v[50:51], v[50:51], v[52:53]
	s_nop 0
	v_pk_mul_f32 v[52:53], v[50:51], v[50:51]
	s_nop 0
	v_add_f32_e32 v49, v52, v62
	v_add_f32_e32 v60, v53, v49
	v_cvt_pk_bf16_f32 v49, v50, v51
	global_store_dwordx2 v[56:57], v[48:49], off offset:32
	s_waitcnt vmcnt(3)
	v_lshlrev_b32_e32 v52, 16, v248
	s_waitcnt vmcnt(7)
	v_lshlrev_b32_e32 v54, 16, v240
	v_and_b32_e32 v55, 0xffff0000, v240
	v_and_b32_e32 v53, 0xffff0000, v248
	v_mul_f32_e32 v48, 0xbfb8aa3b, v54
	v_mul_f32_e32 v44, 0xbfb8aa3b, v55
	v_exp_f32_e32 v48, v48
	v_exp_f32_e32 v44, v44
	v_pk_fma_f32 v[40:41], v[252:253], v[52:53], v[40:41] op_sel_hi:[0,1,1]
	v_add_f32_e32 v48, 1.0, v48
	v_add_f32_e32 v44, 1.0, v44
	v_rcp_f32_e32 v58, v48
	v_rcp_f32_e32 v59, v44
	v_lshlrev_b32_e32 v48, 16, v241
	v_pk_mul_f32 v[44:45], v[58:59], v[54:55]
	s_nop 0
	v_pk_mul_f32 v[40:41], v[40:41], v[44:45]
	s_nop 0
	v_pk_mul_f32 v[44:45], v[40:41], v[40:41]
	v_cvt_pk_bf16_f32 v40, v40, v41
	v_mul_f32_e32 v41, 0xbfb8aa3b, v48
	v_exp_f32_e32 v41, v41
	v_add_f32_e32 v44, v44, v60
	v_add_f32_e32 v52, v45, v44
	v_lshlrev_b32_e32 v44, 16, v249
	v_and_b32_e32 v45, 0xffff0000, v249
	v_and_b32_e32 v49, 0xffff0000, v241
	v_add_f32_e32 v41, 1.0, v41
	v_rcp_f32_e32 v50, v41
	v_mul_f32_e32 v41, 0xbfb8aa3b, v49
	v_exp_f32_e32 v41, v41
	v_pk_fma_f32 v[42:43], v[252:253], v[44:45], v[42:43] op_sel_hi:[0,1,1]
	v_add_f32_e32 v41, 1.0, v41
	v_rcp_f32_e32 v51, v41
	s_nop 0
	v_pk_mul_f32 v[44:45], v[50:51], v[48:49]
	s_nop 0
	v_pk_mul_f32 v[42:43], v[42:43], v[44:45]
	s_nop 0
	v_pk_mul_f32 v[44:45], v[42:43], v[42:43]
	s_nop 0
	v_add_f32_e32 v41, v44, v52
	v_add_f32_e32 v50, v45, v41
	v_cvt_pk_bf16_f32 v41, v42, v43
	global_store_dwordx2 v[56:57], v[40:41], off offset:64
	s_waitcnt vmcnt(3)
	v_lshlrev_b32_e32 v44, 16, v250
	s_waitcnt vmcnt(7)
	v_lshlrev_b32_e32 v46, 16, v242
	v_and_b32_e32 v47, 0xffff0000, v242
	v_and_b32_e32 v45, 0xffff0000, v250
	v_mul_f32_e32 v40, 0xbfb8aa3b, v46
	v_mul_f32_e32 v36, 0xbfb8aa3b, v47
	v_exp_f32_e32 v40, v40
	v_exp_f32_e32 v36, v36
	v_pk_fma_f32 v[32:33], v[252:253], v[44:45], v[32:33] op_sel_hi:[0,1,1]
	v_add_f32_e32 v40, 1.0, v40
	v_add_f32_e32 v36, 1.0, v36
	v_rcp_f32_e32 v48, v40
	v_rcp_f32_e32 v49, v36
	v_lshlrev_b32_e32 v40, 16, v243
	v_pk_mul_f32 v[36:37], v[48:49], v[46:47]
	s_nop 0
	v_pk_mul_f32 v[32:33], v[32:33], v[36:37]
	s_nop 0
	v_pk_mul_f32 v[36:37], v[32:33], v[32:33]
	v_cvt_pk_bf16_f32 v32, v32, v33
	v_mul_f32_e32 v33, 0xbfb8aa3b, v40
	v_exp_f32_e32 v33, v33
	v_add_f32_e32 v36, v36, v50
	v_add_f32_e32 v44, v37, v36
	v_lshlrev_b32_e32 v36, 16, v251
	v_and_b32_e32 v37, 0xffff0000, v251
	v_and_b32_e32 v41, 0xffff0000, v243
	v_add_f32_e32 v33, 1.0, v33
	v_rcp_f32_e32 v42, v33
	v_mul_f32_e32 v33, 0xbfb8aa3b, v41
	v_exp_f32_e32 v33, v33
	v_pk_fma_f32 v[34:35], v[252:253], v[36:37], v[34:35] op_sel_hi:[0,1,1]
	v_add_f32_e32 v33, 1.0, v33
	v_rcp_f32_e32 v43, v33
	s_nop 0
	v_pk_mul_f32 v[36:37], v[42:43], v[40:41]
	s_nop 0
	v_pk_mul_f32 v[34:35], v[34:35], v[36:37]
	s_nop 0
	v_pk_mul_f32 v[36:37], v[34:35], v[34:35]
	s_nop 0
	v_add_f32_e32 v33, v36, v44
	v_add_f32_e32 v121, v37, v33
	v_cvt_pk_bf16_f32 v33, v34, v35
	global_store_dwordx2 v[56:57], v[32:33], off offset:96
	s_barrier
	s_cbranch_scc0 .LBB0_651
	ds_bpermute_b32 v0, v109, v121
	v_lshl_or_b32 v4, v120, 9, v93
	v_readlane_b32 s0, v234, 23
	v_lshlrev_b32_e32 v64, 2, v4
	v_readlane_b32 s1, v234, 24
	s_waitcnt lgkmcnt(0)
	v_add_f32_e32 v5, v121, v0
	ds_bpermute_b32 v6, v110, v5
	v_lshl_add_u64 v[0:1], s[0:1], 0, v[64:65]
	s_mov_b32 s0, 0x800000
	v_add_u32_e32 v2, s73, v92
	v_ashrrev_i32_e32 v3, 31, v2
	s_waitcnt lgkmcnt(0)
	v_add_f32_e32 v5, v5, v6
	v_fmamk_f32 v5, v5, 0x3b000000, v118
	v_mul_f32_e32 v6, 0x4b800000, v5
	v_cmp_gt_f32_e32 vcc, s0, v5
	v_lshlrev_b64 v[2:3], 12, v[2:3]
	v_lshl_or_b32 v2, v4, 1, v2
	v_cndmask_b32_e32 v5, v5, v6, vcc
	v_rsq_f32_e32 v5, v5
	v_readlane_b32 s84, v234, 11
	v_readlane_b32 s86, v234, 13
	v_readlane_b32 s87, v234, 14
	v_mul_f32_e32 v4, 0x45800000, v5
	v_cndmask_b32_e32 v4, v5, v4, vcc
	v_lshl_add_u64 v[2:3], s[86:87], 0, v[2:3]
	v_mov_b32_e32 v5, v4
	s_mov_b64 s[94:95], 0
	v_readlane_b32 s85, v234, 12
